# retention chain: one static s_setprio 1 for waves 4-7 (the half with more MFMA work) for the duration of the chain
# speedup vs baseline: 1.0032x; 1.0032x over previous
; #define LAS __attribute__((address_space(3)))
; template <bool STORE> __device__ __forceinline__ void ret_chain(LAS unsigned char* lds, int b, int h, bf16* Qb, const bf16* Kb, const bf16* Vb, const bf16* Gb, const f32x2* tab, float* s_out) {
;     int tid_ = threadIdx.x; asm volatile("" : "+v"(tid_));
;     const int tid = tid_, lane = tid & 63, w = tid >> 6, wr = w >> 2, wc = w & 3, l15 = lane & 15, quad = lane >> 4;
;     const float lg = LOG_GAMMA[h];
;     float zf_ = 0.f; asm volatile("" : "+v"(zf_)); const f32x4 zero4 = {zf_, zf_, zf_, zf_}; const u32x4 zero4u = __builtin_bit_cast(u32x4, zero4);
;     f32x4 acc_s[4][2];
; #pragma unroll
;     for (int x = 0; x < 4; ++x)
; #pragma unroll
;         for (int y = 0; y < 2; ++y) acc_s[x][y] = zero4;
;     for (int idx = tid; idx < 128 * PTB / 16; idx += NTHREADS) *(LAS u32x4*)(lds + RG3 + idx * 16) = zero4u;
;     ...
;     if (STORE)
; #pragma unroll
;     for (int td = 0; td < 4; ++td)
; #pragma unroll
;         for (int t = 0; t < 2; ++t)
; #pragma unroll
;             for (int r = 0; r < 4; ++r) s_out[(size_t)(64 * wr + 16 * td + 4 * quad + r) * HD + 32 * wc + 16 * t + l15] = acc_s[td][t][r];
;     __syncthreads();
.LBB0_310:
	v_readlane_b32 s0, v255, 21
	v_readlane_b32 s1, v255, 23
	s_add_i32 s0, s1, s0
	s_ashr_i32 s1, s0, 31
	s_lshl_b64 s[0:1], s[0:1], 19
	v_readlane_b32 s4, v255, 19
	s_add_u32 s0, s4, s0
	v_readlane_b32 s4, v255, 20
	s_addc_u32 s1, s4, s1
	v_readlane_b32 s4, v255, 24
	s_lshl_b32 s4, s4, 16
	s_add_u32 s0, s0, s4
	v_or_b32_e32 v0, v220, v219
	s_addc_u32 s1, s1, 0
	v_lshlrev_b32_e32 v188, 2, v192
	s_waitcnt vmcnt(19)
	v_or_b32_e32 v6, 1, v0
	s_waitcnt vmcnt(18)
	v_or_b32_e32 v8, 2, v0
	v_or_b32_e32 v10, 3, v0
	v_lshl_add_u64 v[2:3], s[0:1], 0, v[188:189]
	v_lshlrev_b32_e32 v188, 2, v214
	v_ashrrev_i32_e32 v1, 31, v0
	v_ashrrev_i32_e32 v7, 31, v6
	v_ashrrev_i32_e32 v9, 31, v8
	v_ashrrev_i32_e32 v11, 31, v10
	v_lshl_add_u64 v[2:3], v[2:3], 0, v[188:189]
	v_lshlrev_b64 v[4:5], 9, v[0:1]
	v_lshlrev_b64 v[6:7], 9, v[6:7]
	v_lshlrev_b64 v[8:9], 9, v[8:9]
	v_lshlrev_b64 v[10:11], 9, v[10:11]
	v_lshl_add_u64 v[4:5], v[2:3], 0, v[4:5]
	v_lshl_add_u64 v[6:7], v[2:3], 0, v[6:7]
	v_lshl_add_u64 v[8:9], v[2:3], 0, v[8:9]
	v_lshl_add_u64 v[10:11], v[2:3], 0, v[10:11]
	global_store_dword v[4:5], v80, off
	global_store_dword v[6:7], v81, off
	global_store_dword v[8:9], v82, off
	global_store_dword v[10:11], v83, off
	global_store_dword v[4:5], v76, off offset:64
	global_store_dword v[6:7], v77, off offset:64
	global_store_dword v[8:9], v78, off offset:64
	global_store_dword v[10:11], v79, off offset:64
	v_or_b32_e32 v4, 16, v0
	v_or_b32_e32 v6, 17, v0
	v_or_b32_e32 v8, 18, v0
	v_or_b32_e32 v10, 19, v0
	v_ashrrev_i32_e32 v5, 31, v4
	v_ashrrev_i32_e32 v7, 31, v6
	v_ashrrev_i32_e32 v9, 31, v8
	v_ashrrev_i32_e32 v11, 31, v10
	v_lshlrev_b64 v[4:5], 9, v[4:5]
	v_lshlrev_b64 v[6:7], 9, v[6:7]
	v_lshlrev_b64 v[8:9], 9, v[8:9]
	v_lshlrev_b64 v[10:11], 9, v[10:11]
	v_lshl_add_u64 v[4:5], v[2:3], 0, v[4:5]
	v_lshl_add_u64 v[6:7], v[2:3], 0, v[6:7]
	v_lshl_add_u64 v[8:9], v[2:3], 0, v[8:9]
	v_lshl_add_u64 v[10:11], v[2:3], 0, v[10:11]
	global_store_dword v[4:5], v72, off
	global_store_dword v[6:7], v73, off
	global_store_dword v[8:9], v74, off
	global_store_dword v[10:11], v75, off
	global_store_dword v[4:5], v68, off offset:64
	global_store_dword v[6:7], v69, off offset:64
	global_store_dword v[8:9], v70, off offset:64
	global_store_dword v[10:11], v71, off offset:64
	v_or_b32_e32 v4, 32, v0
	v_or_b32_e32 v6, 33, v0
	v_or_b32_e32 v8, 34, v0
	v_or_b32_e32 v10, 35, v0
	v_ashrrev_i32_e32 v5, 31, v4
	v_ashrrev_i32_e32 v7, 31, v6
	v_ashrrev_i32_e32 v9, 31, v8
	v_ashrrev_i32_e32 v11, 31, v10
	v_lshlrev_b64 v[4:5], 9, v[4:5]
	v_lshlrev_b64 v[6:7], 9, v[6:7]
	v_lshlrev_b64 v[8:9], 9, v[8:9]
	v_lshlrev_b64 v[10:11], 9, v[10:11]
	v_lshl_add_u64 v[4:5], v[2:3], 0, v[4:5]
	v_lshl_add_u64 v[6:7], v[2:3], 0, v[6:7]
	v_lshl_add_u64 v[8:9], v[2:3], 0, v[8:9]
	v_lshl_add_u64 v[10:11], v[2:3], 0, v[10:11]
	global_store_dword v[4:5], v64, off
	global_store_dword v[6:7], v65, off
	global_store_dword v[8:9], v66, off
	global_store_dword v[10:11], v67, off
	global_store_dword v[4:5], v60, off offset:64
	global_store_dword v[6:7], v61, off offset:64
	global_store_dword v[8:9], v62, off offset:64
	global_store_dword v[10:11], v63, off offset:64
	v_or_b32_e32 v4, 48, v0
	v_or_b32_e32 v6, 49, v0
	v_or_b32_e32 v8, 50, v0
	v_or_b32_e32 v0, 51, v0
	v_ashrrev_i32_e32 v5, 31, v4
	v_ashrrev_i32_e32 v7, 31, v6
	v_ashrrev_i32_e32 v9, 31, v8
	v_ashrrev_i32_e32 v1, 31, v0
	v_readlane_b32 s0, v254, 0
	v_readlane_b32 s7, v255, 22
	v_lshlrev_b64 v[4:5], 9, v[4:5]
	v_lshlrev_b64 v[6:7], 9, v[6:7]
	v_lshlrev_b64 v[8:9], 9, v[8:9]
	v_lshlrev_b64 v[0:1], 9, v[0:1]
	s_add_i32 s7, s7, s0
	v_lshl_add_u64 v[4:5], v[2:3], 0, v[4:5]
	v_lshl_add_u64 v[6:7], v[2:3], 0, v[6:7]
	v_lshl_add_u64 v[8:9], v[2:3], 0, v[8:9]
	v_lshl_add_u64 v[0:1], v[2:3], 0, v[0:1]
	s_cmp_gt_i32 s7, 63
	global_store_dword v[4:5], v56, off
	global_store_dword v[6:7], v57, off
	global_store_dword v[8:9], v58, off
	global_store_dword v[0:1], v59, off
	global_store_dword v[4:5], v52, off offset:64
	global_store_dword v[6:7], v53, off offset:64
	global_store_dword v[8:9], v54, off offset:64
	global_store_dword v[0:1], v55, off offset:64
	s_setprio 0
	s_waitcnt lgkmcnt(0)
	s_barrier
	v_readlane_b32 s1, v254, 1
	s_cbranch_scc1 .LBB0_465
.LBB0_311:
	v_mov_b32_e32 v53, v193
	v_readfirstlane_b32 s98, v193
	s_nop 1
	s_cmp_ge_u32 s98, 0x100
	s_cbranch_scc0 .Lchain_noprio
	s_setprio 1
.Lchain_noprio:
	s_movk_i32 s0, 0x87f
	v_mov_b32_e32 v0, v189
	v_cmp_lt_i32_e32 vcc, s0, v53
	v_lshlrev_b32_e32 v54, 4, v53
	s_and_saveexec_b64 s[0:1], vcc
	s_xor_b64 s[0:1], exec, s[0:1]
	v_lshlrev_b32_e32 v54, 4, v53
	s_or_saveexec_b64 s[0:1], s[0:1]
	s_and_b32 s8, s7, 7
	s_lshl_b32 s6, s8, 2
	s_getpc_b64 s[4:5]
	s_add_u32 s4, s4, _ZL9LOG_GAMMA@rel32@lo+4
	s_addc_u32 s5, s5, _ZL9LOG_GAMMA@rel32@hi+12
	s_load_dword s33, s[4:5], s6 offset:0x0
	v_mov_b32_e32 v1, v0
	v_mov_b32_e32 v2, v0
	v_mov_b32_e32 v3, v0
	s_xor_b64 exec, exec, s[0:1]
	s_cbranch_execz .LBB0_317
	v_readlane_b32 s4, v254, 60
	v_add_u32_e32 v4, 0xfffffe00, v53
	s_nop 0
	v_add_u32_e32 v5, s4, v54
	s_mov_b64 s[4:5], 0
